# attention: next item's first-pass Q fragments prefetched during the local half; item head copies them (Q round trip and store acknowledgements off the critical path)
# baseline (speedup 1.0000x reference)
; #define AH_LDK(c, bufi) do { kf[bufi][0] = *(const LAS bf16x8*)(lds + kaddr0 + (c) * kcs); kf[bufi][1] = *(const LAS bf16x8*)(lds + kaddr1 + (c) * kcs); \
;         kf[bufi][2] = *(const LAS bf16x8*)(lds + kaddr0 + (c) * kcs + 512); kf[bufi][3] = *(const LAS bf16x8*)(lds + kaddr1 + (c) * kcs + 512); } while (0)
; template <bool LOC> ...
;     ...
;     AH_LDK(0, 0);
; #pragma unroll
;     for (int c = 0; c < 8; ++c) {
;         if (c < 7) AH_LDK(c + 1, (c + 1) & 1);
;         __builtin_amdgcn_sched_barrier(0);
;         f32x4 t0 = (f32x4){0.f, 0.f, 0.f, 0.f}, t1 = (f32x4){0.f, 0.f, 0.f, 0.f};
;         t0 = __builtin_amdgcn_mfma_f32_16x16x32_bf16(kf[c & 1][0], q0, t0, 0, 0, 0); t1 = __builtin_amdgcn_mfma_f32_16x16x32_bf16(kf[c & 1][2], q0, t1, 0, 0, 0);
;         t0 = __builtin_amdgcn_mfma_f32_16x16x32_bf16(kf[c & 1][1], q1, t0, 0, 0, 0); t1 = __builtin_amdgcn_mfma_f32_16x16x32_bf16(kf[c & 1][3], q1, t1, 0, 0, 0);
; #pragma unroll
;         for (int e = 0; e < 8; ++e) { const float a = (e < 4) ? t0[e] : t1[e - 4];
;             if (LOC) { const float bv = bp[c * RPB_PITCH + e]; const bool ok = (e >= elo) && (e < elo + 16); s[c][e] = ok ? (a * SC + bv) : -INFINITY; }
;             else s[c][e] = a * SC; }
;         __builtin_amdgcn_sched_barrier(0);
;     }
.LBB0_296:
	s_or_b64 exec, exec, s[68:69]
	v_mov_b32_e32 v216, 0x3e38aa3b
	v_mov_b32_e32 v217, 0x3e38aa3b
	s_add_i32 s64, s64, -4
	s_min_u32 s64, s64, 56
	v_sub_u32_e32 v36, s64, v26
	v_lshl_add_u32 v24, v36, 13, v128
	v_add_u32_e32 v25, v24, v126
	s_waitcnt lgkmcnt(0)
	s_barrier
	v_add_u32_e32 v26, v24, v127
	ds_read_b128 v[30:33], v25
	ds_read_b128 v[38:41], v25 offset:512
	ds_read_b128 v[42:45], v26
	ds_read_b128 v[46:49], v26 offset:512
	ds_read_b128 v[50:53], v25 offset:8192
	ds_read_b128 v[54:57], v25 offset:8704
	ds_read_b128 v[58:61], v26 offset:8192
	ds_read_b128 v[62:65], v26 offset:8704
	s_sub_i32 s63, s64, s63
	v_lshl_add_u32 v24, s63, 8, v129
	v_add_u32_e32 v232, 0x77c, v24
	v_add_u32_e32 v233, 0xb7c, v24
	s_waitcnt lgkmcnt(7)
	v_mfma_f32_16x16x32_bf16 v[30:33], v[30:33], v[4:7], 0
	ds_read2_b32 v[34:35], v232 offset0:0 offset1:1
	s_waitcnt lgkmcnt(5)
	v_mfma_f32_16x16x32_bf16 v[30:33], v[42:45], v[0:3], v[30:33]
	v_mfma_f32_16x16x32_bf16 v[38:41], v[38:41], v[4:7], 0
	v_mfma_f32_16x16x32_bf16 v[38:41], v[46:49], v[0:3], v[38:41]
	ds_read2_b32 v[210:211], v232 offset0:2 offset1:3
	ds_read2_b32 v[212:213], v232 offset0:4 offset1:5
	ds_read2_b32 v[214:215], v232 offset0:6 offset1:7
	s_waitcnt lgkmcnt(0)
	s_nop 3
	v_pk_fma_f32 v[34:35], v[30:31], v[216:217], v[34:35]
	v_cndmask_b32_e64 v30, v222, v34, s[6:7]
	v_cndmask_b32_e64 v29, v222, v35, s[8:9]
	v_pk_fma_f32 v[210:211], v[32:33], v[216:217], v[210:211]
	v_cndmask_b32_e64 v32, v222, v210, s[10:11]
	v_cndmask_b32_e64 v31, v222, v211, s[12:13]
	v_pk_fma_f32 v[212:213], v[38:39], v[216:217], v[212:213]
	v_cndmask_b32_e64 v34, v222, v212, s[14:15]
	v_cndmask_b32_e64 v33, v222, v213, s[16:17]
	v_pk_fma_f32 v[214:215], v[40:41], v[216:217], v[214:215]
	v_cndmask_b32_e64 v43, v222, v214, s[18:19]
	v_cndmask_b32_e64 v41, v222, v215, s[20:21]
	ds_read_b128 v[44:47], v25 offset:16384
	ds_read_b128 v[66:69], v25 offset:16896
	ds_read_b128 v[100:103], v26 offset:16384
	ds_read_b128 v[152:155], v26 offset:16896
	v_mfma_f32_16x16x32_bf16 v[48:51], v[50:53], v[4:7], 0
	ds_read2_b32 v[38:39], v232 offset0:64 offset1:65
	v_mfma_f32_16x16x32_bf16 v[48:51], v[58:61], v[0:3], v[48:51]
	v_mfma_f32_16x16x32_bf16 v[52:55], v[54:57], v[4:7], 0
	v_mfma_f32_16x16x32_bf16 v[52:55], v[62:65], v[0:3], v[52:55]
	ds_read2_b32 v[210:211], v232 offset0:66 offset1:67
	ds_read2_b32 v[212:213], v232 offset0:68 offset1:69
	ds_read2_b32 v[214:215], v232 offset0:70 offset1:71
	s_waitcnt lgkmcnt(0)
	s_nop 4
	v_pk_fma_f32 v[38:39], v[48:49], v[216:217], v[38:39]
	v_cndmask_b32_e64 v37, v222, v38, s[6:7]
	v_cndmask_b32_e64 v35, v222, v39, s[8:9]
	v_pk_fma_f32 v[210:211], v[50:51], v[216:217], v[210:211]
	v_cndmask_b32_e64 v39, v222, v210, s[10:11]
	v_cndmask_b32_e64 v38, v222, v211, s[12:13]
	v_pk_fma_f32 v[212:213], v[52:53], v[216:217], v[212:213]
	v_cndmask_b32_e64 v42, v222, v212, s[14:15]
	v_cndmask_b32_e64 v40, v222, v213, s[16:17]
	v_pk_fma_f32 v[214:215], v[54:55], v[216:217], v[214:215]
	v_cndmask_b32_e64 v51, v222, v214, s[18:19]
	v_cndmask_b32_e64 v49, v222, v215, s[20:21]
	ds_read_b128 v[52:55], v25 offset:24576
	ds_read_b128 v[60:63], v25 offset:25088
	ds_read_b128 v[170:173], v26 offset:24576
	ds_read_b128 v[174:177], v26 offset:25088
	v_mfma_f32_16x16x32_bf16 v[44:47], v[44:47], v[4:7], 0
	v_mfma_f32_16x16x32_bf16 v[56:59], v[66:69], v[4:7], 0
	v_mfma_f32_16x16x32_bf16 v[64:67], v[100:103], v[0:3], v[44:47]
	s_nop 4
	ds_read2_b32 v[46:47], v232 offset0:128 offset1:129
	v_mfma_f32_16x16x32_bf16 v[68:71], v[152:155], v[0:3], v[56:59]
	ds_read2_b32 v[210:211], v232 offset0:130 offset1:131
	ds_read2_b32 v[212:213], v232 offset0:132 offset1:133
	ds_read2_b32 v[214:215], v232 offset0:134 offset1:135
	s_waitcnt lgkmcnt(0)
	v_pk_fma_f32 v[46:47], v[64:65], v[216:217], v[46:47]
	v_cndmask_b32_e64 v45, v222, v46, s[6:7]
	v_cndmask_b32_e64 v44, v222, v47, s[8:9]
	v_pk_fma_f32 v[210:211], v[66:67], v[216:217], v[210:211]
	v_cndmask_b32_e64 v47, v222, v210, s[10:11]
	v_cndmask_b32_e64 v46, v222, v211, s[12:13]
	v_pk_fma_f32 v[212:213], v[68:69], v[216:217], v[212:213]
	v_cndmask_b32_e64 v50, v222, v212, s[14:15]
	v_cndmask_b32_e64 v48, v222, v213, s[16:17]
	v_pk_fma_f32 v[214:215], v[70:71], v[216:217], v[214:215]
	v_cndmask_b32_e64 v59, v222, v214, s[18:19]
	v_cndmask_b32_e64 v57, v222, v215, s[20:21]
	ds_read_b128 v[68:71], v25 offset:32768
	ds_read_b128 v[100:103], v25 offset:33280
	ds_read_b128 v[152:155], v26 offset:32768
	ds_read_b128 v[178:181], v26 offset:33280
	v_mfma_f32_16x16x32_bf16 v[52:55], v[52:55], v[4:7], 0
	v_mfma_f32_16x16x32_bf16 v[64:67], v[170:173], v[0:3], v[52:55]
	v_mfma_f32_16x16x32_bf16 v[60:63], v[60:63], v[4:7], 0
	s_nop 4
	ds_read2_b32 v[54:55], v232 offset0:192 offset1:193
	ds_read2_b32 v[210:211], v232 offset0:194 offset1:195
	ds_read2_b32 v[212:213], v232 offset0:196 offset1:197
	ds_read2_b32 v[214:215], v232 offset0:198 offset1:199
	s_waitcnt lgkmcnt(0)
	v_pk_fma_f32 v[54:55], v[64:65], v[216:217], v[54:55]
	v_cndmask_b32_e64 v53, v222, v54, s[6:7]
	v_cndmask_b32_e64 v52, v222, v55, s[8:9]
	v_mfma_f32_16x16x32_bf16 v[60:63], v[174:177], v[0:3], v[60:63]
	v_pk_fma_f32 v[210:211], v[66:67], v[216:217], v[210:211]
	v_cndmask_b32_e64 v55, v222, v210, s[10:11]
	v_cndmask_b32_e64 v54, v222, v211, s[12:13]
	s_nop 3
	s_nop 0
	v_pk_fma_f32 v[212:213], v[60:61], v[216:217], v[212:213]
	v_cndmask_b32_e64 v58, v222, v212, s[14:15]
	v_cndmask_b32_e64 v56, v222, v213, s[16:17]
	v_pk_fma_f32 v[214:215], v[62:63], v[216:217], v[214:215]
	v_cndmask_b32_e64 v67, v222, v214, s[18:19]
	v_cndmask_b32_e64 v65, v222, v215, s[20:21]
	ds_read_b128 v[170:173], v25 offset:40960
	ds_read_b128 v[174:177], v25 offset:41472
	ds_read_b128 v[182:185], v26 offset:40960
	ds_read_b128 v[186:189], v26 offset:41472
	v_mfma_f32_16x16x32_bf16 v[60:63], v[68:71], v[4:7], 0
	v_mfma_f32_16x16x32_bf16 v[68:71], v[100:103], v[4:7], 0
	v_mfma_f32_16x16x32_bf16 v[100:103], v[152:155], v[0:3], v[60:63]
	s_nop 4
	ds_read2_b32 v[62:63], v233 offset0:0 offset1:1
	v_mfma_f32_16x16x32_bf16 v[68:71], v[178:181], v[0:3], v[68:71]
	ds_read2_b32 v[210:211], v233 offset0:2 offset1:3
	ds_read2_b32 v[212:213], v233 offset0:4 offset1:5
	ds_read2_b32 v[214:215], v233 offset0:6 offset1:7
	s_waitcnt lgkmcnt(0)
; #define AH_LDK(c, bufi) do { kf[bufi][0] = *(const LAS bf16x8*)(lds + kaddr0 + (c) * kcs); kf[bufi][1] = *(const LAS bf16x8*)(lds + kaddr1 + (c) * kcs); \
;         kf[bufi][2] = *(const LAS bf16x8*)(lds + kaddr0 + (c) * kcs + 512); kf[bufi][3] = *(const LAS bf16x8*)(lds + kaddr1 + (c) * kcs + 512); } while (0)
; template <bool LOC> ...
;     ...
;     for (int c = 0; c < 8; ++c) {
;         if (c < 7) AH_LDK(c + 1, (c + 1) & 1);
;         __builtin_amdgcn_sched_barrier(0);
;         f32x4 t0 = (f32x4){0.f, 0.f, 0.f, 0.f}, t1 = (f32x4){0.f, 0.f, 0.f, 0.f};
;         t0 = __builtin_amdgcn_mfma_f32_16x16x32_bf16(kf[c & 1][0], q0, t0, 0, 0, 0); t1 = __builtin_amdgcn_mfma_f32_16x16x32_bf16(kf[c & 1][2], q0, t1, 0, 0, 0);
;         t0 = __builtin_amdgcn_mfma_f32_16x16x32_bf16(kf[c & 1][1], q1, t0, 0, 0, 0); t1 = __builtin_amdgcn_mfma_f32_16x16x32_bf16(kf[c & 1][3], q1, t1, 0, 0, 0);
; #pragma unroll
;         for (int e = 0; e < 8; ++e) { const float a = (e < 4) ? t0[e] : t1[e - 4];
;             if (LOC) { const float bv = bp[c * RPB_PITCH + e]; const bool ok = (e >= elo) && (e < elo + 16); s[c][e] = ok ? (a * SC + bv) : -INFINITY; }
;             else s[c][e] = a * SC; }
;         __builtin_amdgcn_sched_barrier(0);
;     }
; __device__ __forceinline__ void phase_mixer(const Params& p, LAS unsigned char* lds, int l, bool with_ctx, int G, int tid, int wave, int lane, int rep_attn, int rep_pool) {
;     ...
;                 const int qtok = (ps == 1) ? (b * SEQ + r * 64 + 16 * n + qi) : (ML + b * CT + 16 * (sel * 8 + wave) + qi);
;                 const bf16_t* qp = PB + (size_t)qtok * PBW + 512 + h * 64 + 8 * g;
;                 qA0 = *(const bf16x8*)qp; qA1 = *(const bf16x8*)(qp + 32);
	v_pk_fma_f32 v[62:63], v[100:101], v[216:217], v[62:63]
	v_cndmask_b32_e64 v61, v222, v62, s[6:7]
	v_cndmask_b32_e64 v60, v222, v63, s[8:9]
	v_pk_fma_f32 v[210:211], v[102:103], v[216:217], v[210:211]
	v_cndmask_b32_e64 v63, v222, v210, s[10:11]
	v_cndmask_b32_e64 v62, v222, v211, s[12:13]
	v_pk_fma_f32 v[212:213], v[68:69], v[216:217], v[212:213]
	v_cndmask_b32_e64 v66, v222, v212, s[14:15]
	v_cndmask_b32_e64 v64, v222, v213, s[16:17]
	v_pk_fma_f32 v[214:215], v[70:71], v[216:217], v[214:215]
	v_cndmask_b32_e64 v102, v222, v214, s[18:19]
	v_cndmask_b32_e64 v100, v222, v215, s[20:21]
	ds_read_b128 v[178:181], v25 offset:49152
	ds_read_b128 v[190:193], v25 offset:49664
	ds_read_b128 v[194:197], v26 offset:49152
	ds_read_b128 v[198:201], v26 offset:49664
	v_mfma_f32_16x16x32_bf16 v[68:71], v[170:173], v[4:7], 0
	v_mfma_f32_16x16x32_bf16 v[170:173], v[182:185], v[0:3], v[68:71]
	v_mfma_f32_16x16x32_bf16 v[152:155], v[174:177], v[4:7], 0
	s_nop 4
	ds_read2_b32 v[70:71], v233 offset0:64 offset1:65
	ds_read2_b32 v[210:211], v233 offset0:66 offset1:67
	ds_read2_b32 v[212:213], v233 offset0:68 offset1:69
	ds_read2_b32 v[214:215], v233 offset0:70 offset1:71
	s_waitcnt lgkmcnt(0)
	v_pk_fma_f32 v[70:71], v[170:171], v[216:217], v[70:71]
	v_cndmask_b32_e64 v69, v222, v70, s[6:7]
	v_cndmask_b32_e64 v68, v222, v71, s[8:9]
	v_mfma_f32_16x16x32_bf16 v[174:177], v[186:189], v[0:3], v[152:155]
	v_pk_fma_f32 v[210:211], v[172:173], v[216:217], v[210:211]
	v_cndmask_b32_e64 v71, v222, v210, s[10:11]
	v_cndmask_b32_e64 v70, v222, v211, s[12:13]
	s_nop 3
	s_nop 0
	v_pk_fma_f32 v[212:213], v[174:175], v[216:217], v[212:213]
	v_cndmask_b32_e64 v101, v222, v212, s[14:15]
	v_cndmask_b32_e64 v99, v222, v213, s[16:17]
	v_pk_fma_f32 v[214:215], v[176:177], v[216:217], v[214:215]
	v_cndmask_b32_e64 v155, v222, v214, s[18:19]
	v_cndmask_b32_e64 v153, v222, v215, s[20:21]
	ds_read_b128 v[182:185], v25 offset:57344
	ds_read_b128 v[186:189], v25 offset:57856
	ds_read_b128 v[202:205], v26 offset:57344
	ds_read_b128 v[206:209], v26 offset:57856
	v_mfma_f32_16x16x32_bf16 v[170:173], v[178:181], v[4:7], 0
	ds_read2_b32 v[26:27], v233 offset0:128 offset1:129
	v_mfma_f32_16x16x32_bf16 v[170:173], v[194:197], v[0:3], v[170:173]
	v_mfma_f32_16x16x32_bf16 v[174:177], v[190:193], v[4:7], 0
	v_mfma_f32_16x16x32_bf16 v[174:177], v[198:201], v[0:3], v[174:177]
	ds_read2_b32 v[210:211], v233 offset0:130 offset1:131
	ds_read2_b32 v[212:213], v233 offset0:132 offset1:133
	ds_read2_b32 v[214:215], v233 offset0:134 offset1:135
	s_waitcnt lgkmcnt(0)
	s_nop 4
	v_pk_fma_f32 v[26:27], v[170:171], v[216:217], v[26:27]
	v_cndmask_b32_e64 v104, v222, v26, s[6:7]
	v_cndmask_b32_e64 v103, v222, v27, s[8:9]
	v_pk_fma_f32 v[210:211], v[172:173], v[216:217], v[210:211]
	v_cndmask_b32_e64 v151, v222, v210, s[10:11]
	v_cndmask_b32_e64 v105, v222, v211, s[12:13]
	v_pk_fma_f32 v[212:213], v[174:175], v[216:217], v[212:213]
	v_cndmask_b32_e64 v154, v222, v212, s[14:15]
	v_cndmask_b32_e64 v152, v222, v213, s[16:17]
	v_pk_fma_f32 v[214:215], v[176:177], v[216:217], v[214:215]
	v_cndmask_b32_e64 v175, v222, v214, s[18:19]
	v_cndmask_b32_e64 v173, v222, v215, s[20:21]
	v_mfma_f32_16x16x32_bf16 v[176:179], v[182:185], v[4:7], 0
	v_mfma_f32_16x16x32_bf16 v[4:7], v[186:189], v[4:7], 0
	v_mfma_f32_16x16x32_bf16 v[176:179], v[202:205], v[0:3], v[176:179]
	v_mfma_f32_16x16x32_bf16 v[0:3], v[206:209], v[0:3], v[4:7]
	s_nop 5
	ds_read2_b32 v[4:5], v233 offset0:192 offset1:193
	ds_read2_b32 v[210:211], v233 offset0:194 offset1:195
	ds_read2_b32 v[212:213], v233 offset0:196 offset1:197
	ds_read2_b32 v[214:215], v233 offset0:198 offset1:199
	s_waitcnt lgkmcnt(0)
	v_pk_fma_f32 v[4:5], v[176:177], v[216:217], v[4:5]
	v_cndmask_b32_e64 v170, v222, v4, s[6:7]
	v_cndmask_b32_e64 v167, v222, v5, s[8:9]
	v_pk_fma_f32 v[210:211], v[178:179], v[216:217], v[210:211]
	v_cndmask_b32_e64 v172, v222, v210, s[10:11]
	v_cndmask_b32_e64 v171, v222, v211, s[12:13]
	v_pk_fma_f32 v[212:213], v[0:1], v[216:217], v[212:213]
	v_cndmask_b32_e64 v176, v222, v212, s[14:15]
	v_cndmask_b32_e64 v174, v222, v213, s[16:17]
	v_pk_fma_f32 v[214:215], v[2:3], v[216:217], v[214:215]
	v_cndmask_b32_e64 v178, v222, v214, s[18:19]
	v_cndmask_b32_e64 v177, v222, v215, s[20:21]
	s_barrier
	s_add_i32 s94, s61, s3
	s_cmpk_gt_i32 s94, 0x7ff
	s_cbranch_scc1 .Lm_noctx
	s_lshr_b32 s95, s94, 8
	s_lshl_b32 s95, s95, 8
	s_add_i32 s95, s95, 0x8000
	s_mul_i32 s97, s95, 0xc00
	s_and_b32 s98, s94, 7
	s_lshl_b32 s99, s98, 7
	s_add_i32 s97, s97, s99
	s_add_i32 s97, s97, 0x800
	s_add_u32 s34, s0, s97
	s_addc_u32 s35, s1, 0
	s_lshl_b32 s99, s87, 10
	s_add_i32 m0, s99, 0x0
	s_nop 0
	global_load_lds_dwordx4 v235, s[34:35]
	s_add_u32 s34, s34, 0x30000
	s_addc_u32 s35, s35, 0
	s_add_i32 m0, s99, 0x2000
	s_nop 0
	global_load_lds_dwordx4 v235, s[34:35]
	s_add_u32 s34, s34, 0x30000
	s_addc_u32 s35, s35, 0
	s_add_i32 m0, s99, 0x4000
	s_nop 0
	global_load_lds_dwordx4 v235, s[34:35]
	s_add_u32 s34, s34, 0x30000
	s_addc_u32 s35, s35, 0
	s_add_i32 m0, s99, 0x6000
	s_nop 0
	global_load_lds_dwordx4 v235, s[34:35]
	s_mul_i32 s97, s98, 0x444000
	s_lshl_b32 s95, s95, 1
	s_add_i32 s97, s97, s95
	s_add_u32 s34, s28, s97
	s_addc_u32 s35, s29, 0
	s_add_i32 m0, s99, 0x8000
	s_nop 0
	global_load_lds_dwordx4 v236, s[34:35]
	s_add_u32 s34, s34, 0x111000
	s_addc_u32 s35, s35, 0
	s_add_i32 m0, s99, 0xa000
	s_nop 0
	global_load_lds_dwordx4 v236, s[34:35]
	s_add_u32 s34, s34, 0x111000
	s_addc_u32 s35, s35, 0
	s_add_i32 m0, s99, 0xc000
	s_nop 0
	global_load_lds_dwordx4 v236, s[34:35]
	s_add_u32 s34, s34, 0x111000
	s_addc_u32 s35, s35, 0
	s_add_i32 m0, s99, 0xe000
	s_nop 0
	global_load_lds_dwordx4 v236, s[34:35]
	s_ashr_i32 s95, s94, 8
	s_lshr_b32 s97, s94, 2
	s_and_b32 s97, s97, 62
	s_add_i32 s97, s97, s24
	s_lshl_b32 s97, s97, 6
	s_lshl_b32 s98, s95, 12
	s_add_i32 s97, s97, s98
	s_or_b32 s97, s97, s33
	s_lshr_b32 s98, s94, 3
	s_lshl_b32 s99, s95, 1
	s_sub_i32 s98, s98, s99
	s_and_b32 s98, s98, 31
	s_cmp_lt_u32 s98, 2
	s_cselect_b64 s[34:35], -1, 0
	s_and_b64 s[34:35], s[36:37], s[34:35]
	s_lshl_b32 s98, s98, 7
	s_and_b32 s99, s94, 0xffffff00
	s_add_i32 s99, s99, 0x8000
	s_add_i32 s99, s99, s25
	s_add_i32 s99, s99, s98
	s_and_b64 s[34:35], s[34:35], exec
	s_cselect_b32 s32, s99, s97
	s_and_b32 s34, s94, 7
	s_lshl_b32 s34, s34, 7
	s_mov_b32 s35, 0
	v_or_b32_e32 v212, s32, v107
	v_lshl_add_u64 v[210:211], v[92:93], 0, s[34:35]
	v_mad_i64_i32 v[214:215], s[98:99], v212, s58, v[210:211]
	global_load_dwordx4 v[208:211], v[214:215], off offset:1024
	s_nop 0
	global_load_dwordx4 v[212:215], v[214:215], off offset:1088

; #define LAS __attribute__((address_space(3)))
; __device__ __forceinline__ void phase_mixer(const Params& p, LAS unsigned char* lds, int l, bool with_ctx, int G, int tid, int wave, int lane, int rep_attn, int rep_pool) {
;     ...
;         const int x = I & 7, t = I >> 3, j = t & 31, rho = t >> 5, pr = rho * 8 + x, b = pr >> 3, h = pr & 7;
;         const int r0 = 2 * j, rs0 = min(max(r0 - 4, 0), 56);
;         const int r = r0 + (wave >> 2), n = wave & 3, rs = min(max(r - 4, 0), 56), kc0 = min(max(16 * n - 8, 0), 32);
;         const int qc = 16 * n + qi, qs = min(max(qc - 8, 0), 48);
;         const int sel = (j - 2 * rho) & 31;
;         const int npass = (with_ctx && sel < 2) ? 2 : 1;
;         {
;             u32x4 kreg[4], vreg[4];
;             const bf16_t* ksrc = PB + (size_t)(ML + b * CT + (tid >> 3)) * PBW + 1024 + h * 64 + (tid & 7) * 8;
;             const bf16_t* vsrc = VT + (size_t)(h * 64 + (tid >> 5)) * VTP + ML + b * CT + (tid & 31) * 8;
; #pragma unroll
;             for (int ps = 0; ps < 4; ++ps) { kreg[ps] = *(const u32x4*)(ksrc + (size_t)(ps * 64) * PBW); vreg[ps] = *(const u32x4*)(vsrc + (size_t)(ps * 16) * VTP); }
;             __builtin_amdgcn_sched_barrier(0);
; #pragma unroll
;             for (int ps = 0; ps < 4; ++ps) { const int key = ps * 64 + (tid >> 3), d = ps * 16 + (tid >> 5);
;                 *(LAS u32x4*)(lds + AT_KC + key * 128 + ((((tid & 7) ^ kswz(key))) << 4)) = kreg[ps];
;                 *(LAS u32x4*)(lds + AT_VC + d * 512 + ((((tid & 31) ^ (d & 15))) << 4)) = vreg[ps]; }
;         }
;         __syncthreads();
;         float mxA = -INFINITY, lA = 0.f; f32x4 oA[4]; bf16x8 qA0, qA1;
;         {
;             const int kl = kap, ka0 = AT_KC + kl * 128 + ((g ^ kswz(kl)) << 4), ka1 = AT_KC + kl * 128 + (((g + 4) ^ kswz(kl)) << 4);
;             const int vrow = AT_VC + qi * 512;
; #pragma unroll 1
;             for (int ps = 2 - npass; ps < 2; ++ps) {
;                 const int qtok = (ps == 1) ? (b * SEQ + r * 64 + 16 * n + qi) : (ML + b * CT + 16 * (sel * 8 + wave) + qi);
;                 const bf16_t* qp = PB + (size_t)qtok * PBW + 512 + h * 64 + 8 * g;
;                 qA0 = *(const bf16x8*)qp; qA1 = *(const bf16x8*)(qp + 32);
;     ...
;             const bf16_t* ksrc = PB + (size_t)(tok0 + (tid >> 3)) * PBW + 1024 + h * 64 + (tid & 7) * 8;
;             u32x4 kreg[9], vreg[9];
; #pragma unroll
.LBB0_297:
	s_ashr_i32 s62, s61, 8
	s_lshr_b32 s63, s61, 2
	s_lshr_b32 s30, s61, 3
	s_and_b32 s71, s63, 62
	s_lshl_b32 s68, s62, 1
	s_add_i32 s63, s71, s24
	s_sub_i32 s30, s30, s68
	s_and_b32 s65, s61, 7
	s_max_i32 s64, s63, 4
	s_and_b32 s80, s30, 31
	s_cmp_lt_u32 s80, 2
	s_cselect_b64 s[68:69], -1, 0
	s_and_b32 s74, s61, 0xffffff00
	s_add_i32 s81, s74, 0x8000
	s_lshl_b32 s30, s65, 7
	s_lshl_b32 s70, s65, 6
	s_lshl_b32 s76, s62, 12
	s_lshl_b32 s62, s63, 6
	s_and_b64 s[74:75], s[36:37], s[68:69]
	s_lshl_b32 s68, s80, 7
	s_add_i32 s77, s81, s25
	s_add_i32 s62, s62, s76
	s_add_i32 s77, s77, s68
	s_or_b32 s80, s62, s33
	v_lshl_add_u64 v[100:101], v[92:93], 0, s[30:31]
	v_lshl_add_u64 v[102:103], v[94:95], 0, s[30:31]
	s_and_b64 s[68:69], s[74:75], exec
	s_cselect_b32 s30, s77, s80
	v_or_b32_e32 v104, s30, v107
	s_cmp_eq_u32 s61, s2
	s_cbranch_scc1 .Lq_first
	s_waitcnt vmcnt(4)
	v_mov_b32_e32 v4, v208
	v_mov_b32_e32 v5, v209
	v_mov_b32_e32 v6, v210
	v_mov_b32_e32 v7, v211
	v_mov_b32_e32 v0, v212
	v_mov_b32_e32 v1, v213
	v_mov_b32_e32 v2, v214
	v_mov_b32_e32 v3, v215
	s_barrier
	s_lshr_b32 s94, s61, 8
	s_lshl_b32 s94, s94, 13
	s_sub_i32 s95, s71, 4
	s_max_i32 s95, s95, 0
	s_min_i32 s95, s95, 56
	s_lshl_b32 s95, s95, 7
	s_add_i32 s94, s94, s95
	s_mul_i32 s95, s65, 0x444000
	s_add_i32 s94, s94, s95
	s_add_u32 s34, s28, s94
	s_addc_u32 s35, s29, 0
	s_lshl_b32 s95, s87, 10
	s_add_i32 m0, s95, 0x12000
	s_nop 0
	global_load_lds_dwordx4 v237, s[34:35]
	s_add_i32 m0, s95, 0x14000
	s_nop 0
	global_load_lds_dwordx4 v238, s[34:35]
	s_add_i32 m0, s95, 0x16000
	s_nop 0
	global_load_lds_dwordx4 v239, s[34:35]
	s_add_i32 m0, s95, 0x18000
	s_nop 0
	global_load_lds_dwordx4 v240, s[34:35]
	s_add_i32 m0, s95, 0x1a000
	s_nop 0
	global_load_lds_dwordx4 v241, s[34:35]
	s_add_i32 m0, s95, 0x1c000
	s_nop 0
	global_load_lds_dwordx4 v242, s[34:35]
	s_add_i32 m0, s95, 0x1e000
	s_nop 0
	global_load_lds_dwordx4 v243, s[34:35]
	s_add_i32 m0, s95, 0x20000
	s_nop 0
	global_load_lds_dwordx4 v244, s[34:35]
	s_add_i32 m0, s95, 0x22000
	s_nop 0
	global_load_lds_dwordx4 v245, s[34:35]
	s_add_i32 m0, s95, 0x24000
	s_nop 0
	global_load_lds_dwordx4 v246, s[34:35]
	s_branch .Lqjoin_299
.Lq_first:
	v_mad_i64_i32 v[0:1], s[68:69], v104, s58, v[100:101]
	global_load_dwordx4 v[4:7], v[0:1], off offset:1024
	s_nop 0
	global_load_dwordx4 v[0:3], v[0:1], off offset:1088
	s_waitcnt vmcnt(2)
	s_barrier
	s_lshr_b32 s94, s61, 8
	s_lshl_b32 s94, s94, 13
	s_sub_i32 s95, s71, 4
	s_max_i32 s95, s95, 0
	s_min_i32 s95, s95, 56
	s_lshl_b32 s95, s95, 7
	s_add_i32 s94, s94, s95
	s_mul_i32 s95, s65, 0x444000
	s_add_i32 s94, s94, s95
	s_add_u32 s34, s28, s94
	s_addc_u32 s35, s29, 0
	s_lshl_b32 s95, s87, 10
	s_add_i32 m0, s95, 0x12000
	s_nop 0
	global_load_lds_dwordx4 v237, s[34:35]
	s_add_i32 m0, s95, 0x14000
	s_nop 0
	global_load_lds_dwordx4 v238, s[34:35]
	s_add_i32 m0, s95, 0x16000
	s_nop 0
	global_load_lds_dwordx4 v239, s[34:35]
	s_add_i32 m0, s95, 0x18000
	s_nop 0
	global_load_lds_dwordx4 v240, s[34:35]
	s_add_i32 m0, s95, 0x1a000
	s_nop 0
	global_load_lds_dwordx4 v241, s[34:35]
	s_add_i32 m0, s95, 0x1c000
	s_nop 0
	global_load_lds_dwordx4 v242, s[34:35]
	s_add_i32 m0, s95, 0x1e000
	s_nop 0
	global_load_lds_dwordx4 v243, s[34:35]
	s_add_i32 m0, s95, 0x20000
	s_nop 0
	global_load_lds_dwordx4 v244, s[34:35]
	s_add_i32 m0, s95, 0x22000
	s_nop 0
	global_load_lds_dwordx4 v245, s[34:35]
	s_add_i32 m0, s95, 0x24000
	s_nop 0
	global_load_lds_dwordx4 v246, s[34:35]
	s_waitcnt vmcnt(10)
	s_branch .Lqjoin_299
